# K loop: pointer/LDS-address bookkeeping that followed the last MFMA of four blocks moved into the gaps between MFMAs 9-15 (wave reaches the barrier right behind its last MFMA)
# speedup vs baseline: 1.0068x; 1.0068x over previous
.LBB0_522:
	s_add_i32 vcc_lo, s74, 2
	s_add_u32 s76, s72, 0x80
	s_addc_u32 s75, s73, 0
	s_add_i32 vcc_hi, 0, 0x10000
	v_add_u32_e32 v140, vcc_hi, v237
	s_waitcnt lgkmcnt(0)
	ds_read_b128 v[128:131], v140
	ds_read_b128 v[132:135], v140 offset:1024
	ds_read_b128 v[136:139], v140 offset:2048
	ds_read_b128 v[140:143], v140 offset:3072
	s_cmp_eq_u32 s50, s74
	s_cselect_b32 s74, s68, s76
	s_cselect_b32 s75, s69, s75
	s_cselect_b32 s77, s71, s79
	s_cselect_b32 s76, s70, s78
	v_lshl_add_u64 v[176:177], s[72:73], 0, v[206:207]
	s_add_i32 m0, s93, 0xc000
	ds_read_b128 v[144:147], v240
	ds_read_b128 v[148:151], v240 offset:1024
	ds_read_b128 v[152:155], v240 offset:2048
	ds_read_b128 v[156:159], v240 offset:3072
	ds_read_b128 v[160:163], v240 offset:4096
	ds_read_b128 v[164:167], v240 offset:5120
	ds_read_b128 v[168:171], v240 offset:6144
	ds_read_b128 v[172:175], v240 offset:7168
	global_load_lds_dwordx4 v[176:177], off
	v_lshl_add_u64 v[176:177], s[72:73], 0, v[208:209]
	s_add_i32 m0, s93, 0xe000
	s_nop 0
	global_load_lds_dwordx4 v[176:177], off
	s_waitcnt lgkmcnt(8)
	s_barrier
	s_waitcnt lgkmcnt(0)
	v_mfma_f32_16x16x32_bf16 v[124:127], v[128:131], v[144:147], v[124:127]
	v_mfma_f32_16x16x32_bf16 v[120:123], v[136:139], v[144:147], v[120:123]
	v_mfma_f32_16x16x32_bf16 v[116:119], v[128:131], v[152:155], v[116:119]
	v_mfma_f32_16x16x32_bf16 v[112:115], v[136:139], v[152:155], v[112:115]
	v_mfma_f32_16x16x32_bf16 v[100:103], v[128:131], v[160:163], v[100:103]
	v_mfma_f32_16x16x32_bf16 v[96:99], v[136:139], v[160:163], v[96:99]
	v_mfma_f32_16x16x32_bf16 v[84:87], v[128:131], v[168:171], v[84:87]
	v_mfma_f32_16x16x32_bf16 v[80:83], v[136:139], v[168:171], v[80:83]
	v_mfma_f32_16x16x32_bf16 v[124:127], v[132:135], v[148:151], v[124:127]
	v_mfma_f32_16x16x32_bf16 v[120:123], v[140:143], v[148:151], v[120:123]
	v_mfma_f32_16x16x32_bf16 v[116:119], v[132:135], v[156:159], v[116:119]
	v_mfma_f32_16x16x32_bf16 v[112:115], v[140:143], v[156:159], v[112:115]
	v_mfma_f32_16x16x32_bf16 v[100:103], v[132:135], v[164:167], v[100:103]
	v_mfma_f32_16x16x32_bf16 v[96:99], v[140:143], v[164:167], v[96:99]
	v_mfma_f32_16x16x32_bf16 v[84:87], v[132:135], v[172:175], v[84:87]
	v_mfma_f32_16x16x32_bf16 v[80:83], v[140:143], v[172:175], v[80:83]
	s_barrier
	s_add_i32 s31, 0, 0x14000
	s_add_i32 vcc_hi, vcc_hi, s87
	v_add_u32_e32 v188, s31, v237
	v_lshl_add_u64 v[210:211], s[76:77], 0, v[196:197]
	s_mov_b32 m0, vcc_hi
	ds_read_b128 v[176:179], v188
	ds_read_b128 v[180:183], v188 offset:1024
	ds_read_b128 v[184:187], v188 offset:2048
	ds_read_b128 v[188:191], v188 offset:3072
	global_load_lds_dwordx4 v[210:211], off
	v_lshl_add_u64 v[212:213], s[76:77], 0, v[200:201]
	s_add_i32 m0, vcc_hi, 0x2000
	s_nop 0
	global_load_lds_dwordx4 v[212:213], off
	s_barrier
	s_waitcnt lgkmcnt(0)
	v_mfma_f32_16x16x32_bf16 v[108:111], v[176:179], v[144:147], v[108:111]
	v_mfma_f32_16x16x32_bf16 v[104:107], v[184:187], v[144:147], v[104:107]
	v_mfma_f32_16x16x32_bf16 v[92:95], v[176:179], v[152:155], v[92:95]
	v_mfma_f32_16x16x32_bf16 v[88:91], v[184:187], v[152:155], v[88:91]
	v_mfma_f32_16x16x32_bf16 v[76:79], v[176:179], v[160:163], v[76:79]
	v_mfma_f32_16x16x32_bf16 v[72:75], v[184:187], v[160:163], v[72:75]
	v_mfma_f32_16x16x32_bf16 v[68:71], v[176:179], v[168:171], v[68:71]
	v_mfma_f32_16x16x32_bf16 v[64:67], v[184:187], v[168:171], v[64:67]
	v_mfma_f32_16x16x32_bf16 v[108:111], v[180:183], v[148:151], v[108:111]
	s_mov_b32 m0, s93
	v_mfma_f32_16x16x32_bf16 v[104:107], v[188:191], v[148:151], v[104:107]
	v_lshl_add_u64 v[214:215], s[74:75], 0, v[194:195]
	v_mfma_f32_16x16x32_bf16 v[92:95], v[180:183], v[156:159], v[92:95]
	v_mfma_f32_16x16x32_bf16 v[88:91], v[188:191], v[156:159], v[88:91]
	v_mfma_f32_16x16x32_bf16 v[76:79], v[180:183], v[164:167], v[76:79]
	v_mfma_f32_16x16x32_bf16 v[72:75], v[188:191], v[164:167], v[72:75]
	v_mfma_f32_16x16x32_bf16 v[68:71], v[180:183], v[172:175], v[68:71]
	v_mfma_f32_16x16x32_bf16 v[64:67], v[188:191], v[172:175], v[64:67]
	s_barrier
	ds_read_b128 v[144:147], v240 offset:16384
	ds_read_b128 v[148:151], v240 offset:17408
	ds_read_b128 v[152:155], v240 offset:18432
	ds_read_b128 v[156:159], v240 offset:19456
	ds_read_b128 v[160:163], v240 offset:20480
	ds_read_b128 v[164:167], v240 offset:21504
	ds_read_b128 v[168:171], v240 offset:22528
	ds_read_b128 v[172:175], v240 offset:23552
	global_load_lds_dwordx4 v[214:215], off
	v_lshl_add_u64 v[216:217], s[74:75], 0, v[198:199]
	s_mov_b32 m0, s54
	s_nop 0
	global_load_lds_dwordx4 v[216:217], off
	s_barrier
	s_waitcnt lgkmcnt(0)
	v_mfma_f32_16x16x32_bf16 v[60:63], v[128:131], v[144:147], v[60:63]
	v_mfma_f32_16x16x32_bf16 v[56:59], v[136:139], v[144:147], v[56:59]
	v_mfma_f32_16x16x32_bf16 v[52:55], v[128:131], v[152:155], v[52:55]
	v_mfma_f32_16x16x32_bf16 v[48:51], v[136:139], v[152:155], v[48:51]
	v_mfma_f32_16x16x32_bf16 v[36:39], v[128:131], v[160:163], v[36:39]
	v_mfma_f32_16x16x32_bf16 v[32:35], v[136:139], v[160:163], v[32:35]
	v_mfma_f32_16x16x32_bf16 v[20:23], v[128:131], v[168:171], v[20:23]
	v_mfma_f32_16x16x32_bf16 v[16:19], v[136:139], v[168:171], v[16:19]
	v_mfma_f32_16x16x32_bf16 v[60:63], v[132:135], v[148:151], v[60:63]
	v_mfma_f32_16x16x32_bf16 v[56:59], v[140:143], v[148:151], v[56:59]
	v_mfma_f32_16x16x32_bf16 v[52:55], v[132:135], v[156:159], v[52:55]
	v_mfma_f32_16x16x32_bf16 v[48:51], v[140:143], v[156:159], v[48:51]
	v_mfma_f32_16x16x32_bf16 v[36:39], v[132:135], v[164:167], v[36:39]
	v_mfma_f32_16x16x32_bf16 v[32:35], v[140:143], v[164:167], v[32:35]
	v_mfma_f32_16x16x32_bf16 v[20:23], v[132:135], v[172:175], v[20:23]
	v_mfma_f32_16x16x32_bf16 v[16:19], v[140:143], v[172:175], v[16:19]
	s_barrier
	s_add_u32 s76, s76, s20
	s_addc_u32 s77, s77, 0
	s_add_i32 s31, s31, s87
	v_lshl_add_u64 v[218:219], s[76:77], 0, v[196:197]
	s_mov_b32 m0, s31
	v_lshl_add_u64 v[220:221], s[76:77], 0, v[200:201]
	global_load_lds_dwordx4 v[218:219], off
	s_add_i32 m0, s31, 0x2000
	s_nop 0
	global_load_lds_dwordx4 v[220:221], off
	s_waitcnt vmcnt(6)
	s_barrier
	v_mfma_f32_16x16x32_bf16 v[44:47], v[176:179], v[144:147], v[44:47]
	v_mfma_f32_16x16x32_bf16 v[40:43], v[184:187], v[144:147], v[40:43]
	v_mfma_f32_16x16x32_bf16 v[28:31], v[176:179], v[152:155], v[28:31]
	v_mfma_f32_16x16x32_bf16 v[24:27], v[184:187], v[152:155], v[24:27]
	v_mfma_f32_16x16x32_bf16 v[12:15], v[176:179], v[160:163], v[12:15]
	v_mfma_f32_16x16x32_bf16 v[8:11], v[184:187], v[160:163], v[8:11]
	v_mfma_f32_16x16x32_bf16 v[4:7], v[176:179], v[168:171], v[4:7]
	v_mfma_f32_16x16x32_bf16 v[0:3], v[184:187], v[168:171], v[0:3]
	v_mfma_f32_16x16x32_bf16 v[44:47], v[180:183], v[148:151], v[44:47]
	s_add_i32 s31, 0, 0x18000
	v_mfma_f32_16x16x32_bf16 v[40:43], v[188:191], v[148:151], v[40:43]
	v_add_u32_e32 v140, s31, v237
	v_mfma_f32_16x16x32_bf16 v[28:31], v[180:183], v[156:159], v[28:31]
	v_mfma_f32_16x16x32_bf16 v[24:27], v[188:191], v[156:159], v[24:27]
	v_mfma_f32_16x16x32_bf16 v[12:15], v[180:183], v[164:167], v[12:15]
	v_mfma_f32_16x16x32_bf16 v[8:11], v[188:191], v[164:167], v[8:11]
	v_mfma_f32_16x16x32_bf16 v[4:7], v[180:183], v[172:175], v[4:7]
	v_mfma_f32_16x16x32_bf16 v[0:3], v[188:191], v[172:175], v[0:3]
	s_barrier
	ds_read_b128 v[128:131], v140
	ds_read_b128 v[132:135], v140 offset:1024
	ds_read_b128 v[136:139], v140 offset:2048
	ds_read_b128 v[140:143], v140 offset:3072
	s_add_u32 s74, s74, s20
	s_addc_u32 s75, s75, 0
	s_mov_b32 m0, s34
	v_lshl_add_u64 v[176:177], s[74:75], 0, v[194:195]
	ds_read_b128 v[144:147], v240 offset:32768
	ds_read_b128 v[148:151], v240 offset:33792
	ds_read_b128 v[152:155], v240 offset:34816
	ds_read_b128 v[156:159], v240 offset:35840
	ds_read_b128 v[160:163], v240 offset:36864
	ds_read_b128 v[164:167], v240 offset:37888
	ds_read_b128 v[168:171], v240 offset:38912
	ds_read_b128 v[172:175], v240 offset:39936
	global_load_lds_dwordx4 v[176:177], off
	v_lshl_add_u64 v[176:177], s[74:75], 0, v[198:199]
	s_mov_b32 m0, s35
	s_nop 0
	global_load_lds_dwordx4 v[176:177], off
	s_waitcnt lgkmcnt(8)
	s_barrier
	s_waitcnt lgkmcnt(0)
	v_mfma_f32_16x16x32_bf16 v[124:127], v[128:131], v[144:147], v[124:127]
	v_mfma_f32_16x16x32_bf16 v[120:123], v[136:139], v[144:147], v[120:123]
	v_mfma_f32_16x16x32_bf16 v[116:119], v[128:131], v[152:155], v[116:119]
	v_mfma_f32_16x16x32_bf16 v[112:115], v[136:139], v[152:155], v[112:115]
	v_mfma_f32_16x16x32_bf16 v[100:103], v[128:131], v[160:163], v[100:103]
	v_mfma_f32_16x16x32_bf16 v[96:99], v[136:139], v[160:163], v[96:99]
	v_mfma_f32_16x16x32_bf16 v[84:87], v[128:131], v[168:171], v[84:87]
	v_mfma_f32_16x16x32_bf16 v[80:83], v[136:139], v[168:171], v[80:83]
	v_mfma_f32_16x16x32_bf16 v[124:127], v[132:135], v[148:151], v[124:127]
	v_mfma_f32_16x16x32_bf16 v[120:123], v[140:143], v[148:151], v[120:123]
	v_mfma_f32_16x16x32_bf16 v[116:119], v[132:135], v[156:159], v[116:119]
	v_mfma_f32_16x16x32_bf16 v[112:115], v[140:143], v[156:159], v[112:115]
	v_mfma_f32_16x16x32_bf16 v[100:103], v[132:135], v[164:167], v[100:103]
	v_mfma_f32_16x16x32_bf16 v[96:99], v[140:143], v[164:167], v[96:99]
	v_mfma_f32_16x16x32_bf16 v[84:87], v[132:135], v[172:175], v[84:87]
	v_mfma_f32_16x16x32_bf16 v[80:83], v[140:143], v[172:175], v[80:83]
	s_barrier
	s_add_i32 s74, 0, 0x1c000
	s_add_i32 s31, s31, s87
	v_add_u32_e32 v188, s74, v237
	v_lshl_add_u64 v[210:211], v[210:211], 0, s[60:61]
	s_mov_b32 m0, s31
	ds_read_b128 v[176:179], v188
	ds_read_b128 v[180:183], v188 offset:1024
	ds_read_b128 v[184:187], v188 offset:2048
	ds_read_b128 v[188:191], v188 offset:3072
	global_load_lds_dwordx4 v[210:211], off
	v_lshl_add_u64 v[210:211], v[212:213], 0, s[60:61]
	s_add_i32 m0, s31, 0x2000
	s_nop 0
	global_load_lds_dwordx4 v[210:211], off
	s_barrier
	s_waitcnt lgkmcnt(0)
	v_mfma_f32_16x16x32_bf16 v[108:111], v[176:179], v[144:147], v[108:111]
	v_mfma_f32_16x16x32_bf16 v[104:107], v[184:187], v[144:147], v[104:107]
	v_mfma_f32_16x16x32_bf16 v[92:95], v[176:179], v[152:155], v[92:95]
	v_mfma_f32_16x16x32_bf16 v[88:91], v[184:187], v[152:155], v[88:91]
	v_mfma_f32_16x16x32_bf16 v[76:79], v[176:179], v[160:163], v[76:79]
	v_mfma_f32_16x16x32_bf16 v[72:75], v[184:187], v[160:163], v[72:75]
	v_mfma_f32_16x16x32_bf16 v[68:71], v[176:179], v[168:171], v[68:71]
	v_mfma_f32_16x16x32_bf16 v[64:67], v[184:187], v[168:171], v[64:67]
	v_mfma_f32_16x16x32_bf16 v[108:111], v[180:183], v[148:151], v[108:111]
	s_mov_b32 m0, s97
	v_mfma_f32_16x16x32_bf16 v[104:107], v[188:191], v[148:151], v[104:107]
	v_lshl_add_u64 v[210:211], v[214:215], 0, s[60:61]
	v_mfma_f32_16x16x32_bf16 v[92:95], v[180:183], v[156:159], v[92:95]
	v_mfma_f32_16x16x32_bf16 v[88:91], v[188:191], v[156:159], v[88:91]
	v_mfma_f32_16x16x32_bf16 v[76:79], v[180:183], v[164:167], v[76:79]
	v_mfma_f32_16x16x32_bf16 v[72:75], v[188:191], v[164:167], v[72:75]
	v_mfma_f32_16x16x32_bf16 v[68:71], v[180:183], v[172:175], v[68:71]
	v_mfma_f32_16x16x32_bf16 v[64:67], v[188:191], v[172:175], v[64:67]
	s_barrier
	ds_read_b128 v[144:147], v240 offset:49152
	ds_read_b128 v[148:151], v240 offset:50176
	ds_read_b128 v[152:155], v240 offset:51200
	ds_read_b128 v[156:159], v240 offset:52224
	ds_read_b128 v[160:163], v240 offset:53248
	ds_read_b128 v[164:167], v240 offset:54272
	ds_read_b128 v[168:171], v240 offset:55296
	ds_read_b128 v[172:175], v240 offset:56320
	global_load_lds_dwordx4 v[210:211], off
	v_lshl_add_u64 v[210:211], v[216:217], 0, s[60:61]
	s_mov_b32 m0, s36
	s_nop 0
	global_load_lds_dwordx4 v[210:211], off
	s_barrier
	s_waitcnt lgkmcnt(0)
	v_mfma_f32_16x16x32_bf16 v[60:63], v[128:131], v[144:147], v[60:63]
	v_mfma_f32_16x16x32_bf16 v[56:59], v[136:139], v[144:147], v[56:59]
	v_mfma_f32_16x16x32_bf16 v[52:55], v[128:131], v[152:155], v[52:55]
	v_mfma_f32_16x16x32_bf16 v[48:51], v[136:139], v[152:155], v[48:51]
	v_mfma_f32_16x16x32_bf16 v[36:39], v[128:131], v[160:163], v[36:39]
	v_mfma_f32_16x16x32_bf16 v[32:35], v[136:139], v[160:163], v[32:35]
	v_mfma_f32_16x16x32_bf16 v[20:23], v[128:131], v[168:171], v[20:23]
	v_mfma_f32_16x16x32_bf16 v[16:19], v[136:139], v[168:171], v[16:19]
	v_mfma_f32_16x16x32_bf16 v[60:63], v[132:135], v[148:151], v[60:63]
	v_mfma_f32_16x16x32_bf16 v[56:59], v[140:143], v[148:151], v[56:59]
	v_mfma_f32_16x16x32_bf16 v[52:55], v[132:135], v[156:159], v[52:55]
	v_mfma_f32_16x16x32_bf16 v[48:51], v[140:143], v[156:159], v[48:51]
	v_mfma_f32_16x16x32_bf16 v[36:39], v[132:135], v[164:167], v[36:39]
	v_mfma_f32_16x16x32_bf16 v[32:35], v[140:143], v[164:167], v[32:35]
	v_mfma_f32_16x16x32_bf16 v[20:23], v[132:135], v[172:175], v[20:23]
	v_mfma_f32_16x16x32_bf16 v[16:19], v[140:143], v[172:175], v[16:19]
	s_barrier
	s_add_i32 s31, s74, s87
	v_lshl_add_u64 v[128:129], v[218:219], 0, s[60:61]
	s_mov_b32 m0, s31
	s_nop 0
	global_load_lds_dwordx4 v[128:129], off
	v_lshl_add_u64 v[128:129], v[220:221], 0, s[60:61]
	s_add_i32 m0, s31, 0x2000
	s_nop 0
	global_load_lds_dwordx4 v[128:129], off
	s_waitcnt vmcnt(6)
	s_barrier
	v_mfma_f32_16x16x32_bf16 v[44:47], v[176:179], v[144:147], v[44:47]
	v_mfma_f32_16x16x32_bf16 v[40:43], v[184:187], v[144:147], v[40:43]
	v_mfma_f32_16x16x32_bf16 v[28:31], v[176:179], v[152:155], v[28:31]
	v_mfma_f32_16x16x32_bf16 v[24:27], v[184:187], v[152:155], v[24:27]
	v_mfma_f32_16x16x32_bf16 v[12:15], v[176:179], v[160:163], v[12:15]
	v_mfma_f32_16x16x32_bf16 v[8:11], v[184:187], v[160:163], v[8:11]
	v_mfma_f32_16x16x32_bf16 v[4:7], v[176:179], v[168:171], v[4:7]
	v_mfma_f32_16x16x32_bf16 v[0:3], v[184:187], v[168:171], v[0:3]
	v_mfma_f32_16x16x32_bf16 v[44:47], v[180:183], v[148:151], v[44:47]
	s_add_u32 s72, s72, 0x100
	v_mfma_f32_16x16x32_bf16 v[40:43], v[188:191], v[148:151], v[40:43]
	s_addc_u32 s73, s73, 0
	v_mfma_f32_16x16x32_bf16 v[28:31], v[180:183], v[156:159], v[28:31]
	s_add_u32 s78, s78, 0x100
	v_mfma_f32_16x16x32_bf16 v[24:27], v[188:191], v[156:159], v[24:27]
	s_addc_u32 s79, s79, 0
	v_mfma_f32_16x16x32_bf16 v[12:15], v[180:183], v[164:167], v[12:15]
	s_cmp_ge_u32 vcc_lo, s30
	v_mfma_f32_16x16x32_bf16 v[8:11], v[188:191], v[164:167], v[8:11]
	s_mov_b32 s74, vcc_lo
	v_mfma_f32_16x16x32_bf16 v[4:7], v[180:183], v[172:175], v[4:7]
	v_mfma_f32_16x16x32_bf16 v[0:3], v[188:191], v[172:175], v[0:3]
	s_barrier
	s_cbranch_scc0 .LBB0_522
	s_cmp_lt_i32 s91, 0
	s_mov_b64 s[72:73], -1
	s_cbranch_scc0 .LBB0_716
	s_lshl_b32 s78, s46, 8
	s_cmp_lt_i32 s81, 2
	s_cbranch_scc1 .LBB0_582
	s_cmp_lt_i32 s81, 3
	s_cbranch_scc1 .LBB0_579
	s_cmp_lg_u32 s81, 3
	s_cbranch_scc0 .LBB0_544
	v_lshl_or_b32 v128, s19, 7, v238
	v_ashrrev_i32_e32 v129, 31, v128
	v_lshl_add_u64 v[144:145], v[128:129], 1, s[24:25]
	v_and_b32_e32 v129, 64, v231
	v_xor_b32_e32 v128, 16, v231
	v_add_u32_e32 v129, 64, v129
	v_cmp_lt_i32_e32 vcc, v128, v129
	v_add_u32_e32 v146, s78, v202
	v_ashrrev_i32_e32 v147, 31, v146
	v_cndmask_b32_e32 v128, v231, v128, vcc
	v_lshlrev_b32_e32 v167, 2, v128
	v_xor_b32_e32 v128, 32, v231
	v_cmp_lt_i32_e32 vcc, v128, v129
	v_or_b32_e32 v156, 16, v146
	v_ashrrev_i32_e32 v157, 31, v156
	v_cndmask_b32_e32 v128, v231, v128, vcc
	v_lshlrev_b32_e32 v166, 2, v128
	v_lshlrev_b64 v[128:129], 12, v[146:147]
	v_lshl_add_u64 v[160:161], v[144:145], 0, v[128:129]
	global_load_dwordx4 v[140:143], v[160:161], off
	v_or_b32_e32 v152, 32, v146
	v_lshlrev_b64 v[128:129], 12, v[156:157]
	v_ashrrev_i32_e32 v153, 31, v152
	v_or_b32_e32 v148, 48, v146
	v_lshl_add_u64 v[158:159], v[144:145], 0, v[128:129]
	v_lshlrev_b64 v[128:129], 12, v[152:153]
	v_ashrrev_i32_e32 v149, 31, v148
	v_lshl_add_u64 v[154:155], v[144:145], 0, v[128:129]
	v_lshlrev_b64 v[128:129], 12, v[148:149]
	v_lshl_add_u64 v[150:151], v[144:145], 0, v[128:129]
	global_load_dwordx4 v[136:139], v[158:159], off
	global_load_dwordx4 v[132:135], v[154:155], off
	global_load_dwordx4 v[128:131], v[150:151], off
	v_mul_f32_e32 v163, 0xbfb8aa3b, v104
	v_exp_f32_e32 v163, v163
	v_mul_f32_e32 v162, 0xbfb8aa3b, v108
	v_exp_f32_e32 v162, v162
	v_add_f32_e32 v163, 1.0, v163
	v_rcp_f32_e32 v164, v163
	v_mul_f32_e32 v163, 0xbfb8aa3b, v109
	v_exp_f32_e32 v163, v163
	v_add_f32_e32 v162, 1.0, v162
	v_rcp_f32_e32 v162, v162
	v_add_f32_e32 v163, 1.0, v163
	v_rcp_f32_e32 v163, v163
	s_waitcnt vmcnt(0)
	v_lshlrev_b32_e32 v168, 16, v140
	v_and_b32_e32 v169, 0xffff0000, v140
	v_mul_f32_e32 v140, 0xbfb8aa3b, v105
	v_exp_f32_e32 v140, v140
	v_pk_fma_f32 v[162:163], v[162:163], v[124:125], v[168:169]
	v_lshlrev_b32_e32 v168, 16, v142
	v_and_b32_e32 v169, 0xffff0000, v142
	v_add_f32_e32 v140, 1.0, v140
	v_rcp_f32_e32 v165, v140
	v_mul_f32_e32 v140, 0xbfb8aa3b, v110
	v_exp_f32_e32 v140, v140
	v_mul_f32_e32 v142, 0xbfb8aa3b, v111
	v_pk_fma_f32 v[164:165], v[164:165], v[120:121], v[168:169]
	v_lshlrev_b32_e32 v170, 16, v141
	v_add_f32_e32 v140, 1.0, v140
	v_rcp_f32_e32 v168, v140
	v_mul_f32_e32 v140, 0xbfb8aa3b, v106
	v_and_b32_e32 v171, 0xffff0000, v141
	v_mul_f32_e32 v141, 0xbfb8aa3b, v107
	v_exp_f32_e32 v140, v140
	v_exp_f32_e32 v142, v142
	v_exp_f32_e32 v141, v141
	v_add_f32_e32 v140, 1.0, v140
	v_add_f32_e32 v142, 1.0, v142
	v_add_f32_e32 v141, 1.0, v141
	v_rcp_f32_e32 v140, v140
	v_rcp_f32_e32 v169, v142
	v_rcp_f32_e32 v141, v141
	v_lshlrev_b32_e32 v142, 16, v143
	v_and_b32_e32 v143, 0xffff0000, v143
	v_pk_fma_f32 v[168:169], v[168:169], v[126:127], v[170:171]
	v_pk_fma_f32 v[170:171], v[140:141], v[122:123], v[142:143]
	v_cvt_pk_bf16_f32 v140, v162, v163
	v_cvt_pk_bf16_f32 v141, v168, v169
	v_cvt_pk_bf16_f32 v142, v164, v165
	v_cvt_pk_bf16_f32 v143, v170, v171
	global_store_dwordx4 v[160:161], v[140:143], off
	v_pk_mul_f32 v[160:161], v[164:165], v[164:165]
	s_nop 0
	v_pk_mul_f32 v[140:141], v[162:163], v[162:163]
	v_pk_mul_f32 v[142:143], v[168:169], v[168:169]
	v_add_f32_e32 v140, v140, v141
	v_add_f32_e32 v142, v142, v143
	v_pk_mul_f32 v[162:163], v[170:171], v[170:171]
	v_add_f32_e32 v140, v140, v142
	v_add_f32_e32 v141, v160, v161
	v_add_f32_e32 v162, v162, v163
	v_add_f32_e32 v140, v141, v140
	v_add_f32_e32 v140, v162, v140
	v_mov_b32_e32 v141, v140
	s_nop 1
	v_permlane16_swap_b32_e32 v141, v140
	s_waitcnt lgkmcnt(0)
	v_add_f32_e32 v140, v140, v141
	v_mov_b32_e32 v141, v140
	s_nop 1
	v_permlane32_swap_b32_e32 v141, v140
	s_and_saveexec_b64 s[72:73], s[6:7]
	s_cbranch_execz .LBB0_529
	s_waitcnt lgkmcnt(0)
	v_add_f32_e32 v142, v140, v141
	s_lshl_b32 s74, s19, 2
	v_lshlrev_b64 v[140:141], 8, v[146:147]
	s_ashr_i32 s75, s74, 31
	v_lshl_add_u64 v[140:141], s[26:27], 0, v[140:141]
	v_lshl_add_u64 v[140:141], s[74:75], 2, v[140:141]
	s_lshl_b32 s50, s37, 2
	v_lshl_add_u64 v[140:141], v[140:141], 0, s[50:51]
	global_store_dword v[140:141], v142, off
